# MLP-up epilogue: RMS partial-sum loads of row groups 1-6 issued up front into dead fragment registers with counted waits (no store-drain serialisation)
# speedup vs baseline: 1.0104x; 1.0104x over previous
; __device__ __forceinline__ unsigned cvt_pk_bf16(float lo, float hi) { const f32x2c_t v = {lo, hi}; const bf16x2c_t b = __builtin_convertvector(v, bf16x2c_t); return __builtin_bit_cast(unsigned, b); }
;     __device__ __forceinline__ void operator()(const f32x4 (&acc)[2][2][4][2], const Unit& u, int wr, int wc, int fr, int fq) const {
;         const int row0 = u.pm * BM + wr * 64 + fr, col0 = u.pn * BM + wc * 32 + 8 * fq;
; #pragma unroll
;         for (int ai = 0; ai < 2; ++ai)
; #pragma unroll
;             for (int m = 0; m < 4; ++m) { const size_t row = (size_t)(row0 + ai * HALF + m * 16);
;                 const f32x4* sp = (const f32x4*)(SS + row * 32) + 2 * fq; float s;
;                 { const f32x4 t0 = sp[0], t1 = sp[1]; s = ((t0[0] + t0[1]) + (t0[2] + t0[3])) + ((t1[0] + t1[1]) + (t1[2] + t1[3])); }
;                 s += __shfl_xor(s, 16); s += __shfl_xor(s, 32);
;                 const float rstd = 1.0f / sqrtf(s * (1.0f / DM) + NORM_EPS);
; #pragma unroll
;                 for (int bj = 0; bj < 2; ++bj) { f32x4 v0 = acc[ai][bj][m][0] * rstd, v1 = acc[ai][bj][m][1] * rstd;
; #pragma unroll
;                     for (int e = 0; e < 4; ++e) { const float a = fmaxf(v0[e], 0.f), b = fmaxf(v1[e], 0.f); v0[e] = a * a; v1[e] = b * b; }
;                     u32x4 w; w.x = cvt_pk_bf16(v0[0], v0[1]); w.y = cvt_pk_bf16(v0[2], v0[3]); w.z = cvt_pk_bf16(v1[0], v1[1]); w.w = cvt_pk_bf16(v1[2], v1[3]);
;                     *(u32x4*)(H + row * DFF + col0 + bj * HALF) = w; } }
.LBB0_79:
	v_xor_b32_e32 v159, 16, v192
	v_add_u32_e32 v163, 64, v193
	v_cmp_lt_i32_e32 vcc, v159, v163
	v_lshl_add_u32 v158, s34, 8, v1
	v_lshl_or_b32 v172, s28, 8, v160
	v_cndmask_b32_e32 v159, v192, v159, vcc
	v_lshlrev_b32_e32 v162, 2, v159
	v_xor_b32_e32 v159, 32, v192
	v_cmp_lt_i32_e32 vcc, v159, v163
	v_ashrrev_i32_e32 v173, 31, v172
	s_nop 0
	v_cndmask_b32_e32 v159, v192, v159, vcc
	v_lshlrev_b32_e32 v163, 2, v159
	v_ashrrev_i32_e32 v159, 31, v158
	v_lshlrev_b64 v[164:165], 7, v[158:159]
	v_lshl_add_u64 v[168:169], v[152:153], 0, v[164:165]
	global_load_dwordx4 v[164:167], v[168:169], off
	s_nop 0
	global_load_dwordx4 v[168:171], v[168:169], off offset:16
	v_or_b32_e32 v204, 16, v158
	v_ashrrev_i32_e32 v205, 31, v204
	v_lshlrev_b64 v[206:207], 7, v[204:205]
	v_lshl_add_u64 v[206:207], v[152:153], 0, v[206:207]
	global_load_dwordx4 v[208:211], v[206:207], off offset:16
	global_load_dwordx4 v[204:207], v[206:207], off
	v_or_b32_e32 v212, 32, v158
	v_ashrrev_i32_e32 v213, 31, v212
	v_lshlrev_b64 v[214:215], 7, v[212:213]
	v_lshl_add_u64 v[214:215], v[152:153], 0, v[214:215]
	global_load_dwordx4 v[216:219], v[214:215], off offset:16
	global_load_dwordx4 v[212:215], v[214:215], off
	v_or_b32_e32 v220, 48, v158
	v_ashrrev_i32_e32 v221, 31, v220
	v_lshlrev_b64 v[222:223], 7, v[220:221]
	v_lshl_add_u64 v[222:223], v[152:153], 0, v[222:223]
	global_load_dwordx4 v[224:227], v[222:223], off offset:16
	global_load_dwordx4 v[220:223], v[222:223], off
	v_add_u32_e32 v228, 0x80, v158
	v_ashrrev_i32_e32 v229, 31, v228
	v_lshlrev_b64 v[230:231], 7, v[228:229]
	v_lshl_add_u64 v[230:231], v[152:153], 0, v[230:231]
	global_load_dwordx4 v[232:235], v[230:231], off offset:16
	global_load_dwordx4 v[228:231], v[230:231], off
	v_add_u32_e32 v236, 0x90, v158
	v_ashrrev_i32_e32 v237, 31, v236
	v_lshlrev_b64 v[238:239], 7, v[236:237]
	v_lshl_add_u64 v[238:239], v[152:153], 0, v[238:239]
	global_load_dwordx4 v[240:243], v[238:239], off offset:16
	global_load_dwordx4 v[236:239], v[238:239], off
	v_add_u32_e32 v176, 0xa0, v158
	v_ashrrev_i32_e32 v177, 31, v176
	v_lshlrev_b64 v[178:179], 7, v[176:177]
	v_lshl_add_u64 v[178:179], v[152:153], 0, v[178:179]
	global_load_dwordx4 v[180:183], v[178:179], off offset:16
	global_load_dwordx4 v[176:179], v[178:179], off
	s_waitcnt vmcnt(12)
	v_mov_b32_e32 v174, v164
	v_mov_b32_e32 v175, v168
	v_mov_b32_e32 v168, v165
	v_pk_add_f32 v[164:165], v[174:175], v[168:169]
	v_mov_b32_e32 v168, v166
	v_mov_b32_e32 v169, v170
	v_mov_b32_e32 v170, v167
	v_pk_add_f32 v[166:167], v[168:169], v[170:171]
	s_nop 0
	v_pk_add_f32 v[164:165], v[164:165], v[166:167]
	s_nop 0
	v_add_f32_e32 v164, v164, v165
	ds_bpermute_b32 v165, v162, v164
	s_waitcnt lgkmcnt(0)
	v_add_f32_e32 v164, v164, v165
	ds_bpermute_b32 v165, v163, v164
	s_waitcnt lgkmcnt(0)
	v_add_f32_e32 v164, v164, v165
	v_fmamk_f32 v164, v164, 0x3a000000, v190
	v_cmp_gt_f32_e32 vcc, s72, v164
	v_mul_f32_e32 v165, 0x4f800000, v164
	s_nop 0
	v_cndmask_b32_e32 v164, v164, v165, vcc
	v_sqrt_f32_e32 v165, v164
	s_nop 0
	v_add_u32_e32 v166, -1, v165
	v_fma_f32 v167, -v166, v165, v164
	v_cmp_ge_f32_e64 s[0:1], 0, v167
	v_add_u32_e32 v167, 1, v165
	s_nop 0
	v_cndmask_b32_e64 v166, v165, v166, s[0:1]
	v_fma_f32 v165, -v167, v165, v164
	v_cmp_lt_f32_e64 s[0:1], 0, v165
	s_nop 1
	v_cndmask_b32_e64 v165, v166, v167, s[0:1]
	v_mul_f32_e32 v166, 0x37800000, v165
	v_cndmask_b32_e32 v165, v165, v166, vcc
	v_cmp_class_f32_e32 vcc, v164, v191
	s_nop 1
	v_cndmask_b32_e32 v164, v165, v164, vcc
	v_div_scale_f32 v165, s[0:1], v164, v164, 1.0
	v_rcp_f32_e32 v166, v165
	s_nop 0
	v_fma_f32 v167, -v165, v166, 1.0
	v_fmac_f32_e32 v166, v167, v166
	v_div_scale_f32 v167, vcc, 1.0, v164, 1.0
	v_mul_f32_e32 v168, v167, v166
	v_fma_f32 v169, -v165, v168, v167
	v_fmac_f32_e32 v168, v169, v166
	v_fma_f32 v165, -v165, v168, v167
	v_div_fmas_f32 v165, v165, v166, v168
	v_div_fixup_f32 v164, v165, v164, 1.0
	v_pk_mul_f32 v[128:129], v[128:129], v[164:165] op_sel_hi:[1,0]
	v_pk_mul_f32 v[126:127], v[126:127], v[164:165] op_sel_hi:[1,0]
	v_pk_mul_f32 v[122:123], v[122:123], v[164:165] op_sel_hi:[1,0]
	v_pk_mul_f32 v[124:125], v[124:125], v[164:165] op_sel_hi:[1,0]
	v_max_f32_e32 v126, 0, v126
	v_max_f32_e32 v122, 0, v122
	v_max_f32_e32 v127, 0, v127
	v_max_f32_e32 v123, 0, v123
	v_max_f32_e32 v128, 0, v128
	v_max_f32_e32 v129, 0, v129
	v_lshlrev_b64 v[166:167], 14, v[158:159]
	v_pk_mul_f32 v[126:127], v[126:127], v[126:127]
	v_pk_mul_f32 v[122:123], v[122:123], v[122:123]
	v_max_f32_e32 v124, 0, v124
	v_max_f32_e32 v125, 0, v125
	v_pk_mul_f32 v[128:129], v[128:129], v[128:129]
	v_pk_mul_f32 v[168:169], v[124:125], v[124:125]
	v_cvt_pk_bf16_f32 v124, v126, v127
	v_cvt_pk_bf16_f32 v125, v128, v129
	v_cvt_pk_bf16_f32 v126, v122, v123
	v_lshl_add_u64 v[128:129], s[92:93], 0, v[166:167]
	v_lshlrev_b64 v[122:123], 1, v[172:173]
	v_pk_mul_f32 v[114:115], v[114:115], v[164:165] op_sel_hi:[1,0]
	v_cvt_pk_bf16_f32 v127, v168, v169
	v_lshl_add_u64 v[128:129], v[128:129], 0, v[122:123]
	v_pk_mul_f32 v[120:121], v[120:121], v[164:165] op_sel_hi:[1,0]
	v_pk_mul_f32 v[118:119], v[118:119], v[164:165] op_sel_hi:[1,0]
	v_pk_mul_f32 v[116:117], v[116:117], v[164:165] op_sel_hi:[1,0]
	v_max_f32_e32 v114, 0, v114
	v_max_f32_e32 v115, 0, v115
	global_store_dwordx4 v[128:129], v[124:127], off
	v_max_f32_e32 v118, 0, v118
	v_max_f32_e32 v119, 0, v119
	v_pk_mul_f32 v[124:125], v[114:115], v[114:115]
	v_max_f32_e32 v114, 0, v120
	v_max_f32_e32 v116, 0, v116
	v_max_f32_e32 v115, 0, v121
	v_max_f32_e32 v117, 0, v117
	v_pk_mul_f32 v[118:119], v[118:119], v[118:119]
	v_pk_mul_f32 v[120:121], v[114:115], v[114:115]
	v_pk_mul_f32 v[126:127], v[116:117], v[116:117]
	v_cvt_pk_bf16_f32 v114, v118, v119
	v_cvt_pk_bf16_f32 v115, v120, v121
	v_cvt_pk_bf16_f32 v116, v124, v125
	v_cvt_pk_bf16_f32 v117, v126, v127
	global_store_dwordx4 v[128:129], v[114:117], off offset:256
	s_nop 1
	v_or_b32_e32 v114, 16, v158
	v_ashrrev_i32_e32 v115, 31, v114
	v_lshlrev_b64 v[116:117], 7, v[114:115]
	v_lshl_add_u64 v[120:121], v[152:153], 0, v[116:117]
	v_lshlrev_b64 v[114:115], 14, v[114:115]
	s_waitcnt vmcnt(12)
; __device__ __forceinline__ unsigned cvt_pk_bf16(float lo, float hi) { const f32x2c_t v = {lo, hi}; const bf16x2c_t b = __builtin_convertvector(v, bf16x2c_t); return __builtin_bit_cast(unsigned, b); }
;     __device__ __forceinline__ void operator()(const f32x4 (&acc)[2][2][4][2], const Unit& u, int wr, int wc, int fr, int fq) const {
;     ...
;             for (int m = 0; m < 4; ++m) { const size_t row = (size_t)(row0 + ai * HALF + m * 16);
;                 const f32x4* sp = (const f32x4*)(SS + row * 32) + 2 * fq; float s;
;                 { const f32x4 t0 = sp[0], t1 = sp[1]; s = ((t0[0] + t0[1]) + (t0[2] + t0[3])) + ((t1[0] + t1[1]) + (t1[2] + t1[3])); }
;                 s += __shfl_xor(s, 16); s += __shfl_xor(s, 32);
;                 const float rstd = 1.0f / sqrtf(s * (1.0f / DM) + NORM_EPS);
; #pragma unroll
;                 for (int bj = 0; bj < 2; ++bj) { f32x4 v0 = acc[ai][bj][m][0] * rstd, v1 = acc[ai][bj][m][1] * rstd;
; #pragma unroll
;                     for (int e = 0; e < 4; ++e) { const float a = fmaxf(v0[e], 0.f), b = fmaxf(v1[e], 0.f); v0[e] = a * a; v1[e] = b * b; }
;                     u32x4 w; w.x = cvt_pk_bf16(v0[0], v0[1]); w.y = cvt_pk_bf16(v0[2], v0[3]); w.z = cvt_pk_bf16(v1[0], v1[1]); w.w = cvt_pk_bf16(v1[2], v1[3]);
;                     *(u32x4*)(H + row * DFF + col0 + bj * HALF) = w; } }
	v_mov_b32_e32 v116, v204
	v_mov_b32_e32 v117, v205
	v_mov_b32_e32 v118, v206
	v_mov_b32_e32 v119, v207
	v_mov_b32_e32 v124, v208
	v_mov_b32_e32 v125, v209
	v_mov_b32_e32 v126, v210
	v_mov_b32_e32 v127, v211
	v_mov_b32_e32 v120, v116
	v_mov_b32_e32 v121, v124
	v_mov_b32_e32 v124, v117
	v_pk_add_f32 v[116:117], v[120:121], v[124:125]
	v_mov_b32_e32 v120, v118
	v_mov_b32_e32 v121, v126
	v_mov_b32_e32 v126, v119
	v_pk_add_f32 v[118:119], v[120:121], v[126:127]
	s_nop 0
	v_pk_add_f32 v[116:117], v[116:117], v[118:119]
	s_nop 0
	v_add_f32_e32 v116, v116, v117
	ds_bpermute_b32 v117, v162, v116
	s_waitcnt lgkmcnt(0)
	v_add_f32_e32 v116, v116, v117
	ds_bpermute_b32 v117, v163, v116
	s_waitcnt lgkmcnt(0)
	v_add_f32_e32 v116, v116, v117
	v_fmamk_f32 v116, v116, 0x3a000000, v190
	v_cmp_gt_f32_e32 vcc, s72, v116
	v_mul_f32_e32 v117, 0x4f800000, v116
	s_nop 0
	v_cndmask_b32_e32 v116, v116, v117, vcc
	v_sqrt_f32_e32 v117, v116
	s_nop 0
	v_add_u32_e32 v118, -1, v117
	v_fma_f32 v119, -v118, v117, v116
	v_cmp_ge_f32_e64 s[0:1], 0, v119
	v_add_u32_e32 v119, 1, v117
	s_nop 0
	v_cndmask_b32_e64 v118, v117, v118, s[0:1]
	v_fma_f32 v117, -v119, v117, v116
	v_cmp_lt_f32_e64 s[0:1], 0, v117
	s_nop 1
	v_cndmask_b32_e64 v117, v118, v119, s[0:1]
	v_mul_f32_e32 v118, 0x37800000, v117
	v_cndmask_b32_e32 v117, v117, v118, vcc
	v_cmp_class_f32_e32 vcc, v116, v191
	s_nop 1
	v_cndmask_b32_e32 v116, v117, v116, vcc
	v_div_scale_f32 v117, s[0:1], v116, v116, 1.0
	v_rcp_f32_e32 v118, v117
	s_nop 0
	v_fma_f32 v119, -v117, v118, 1.0
	v_fmac_f32_e32 v118, v119, v118
	v_div_scale_f32 v119, vcc, 1.0, v116, 1.0
	v_mul_f32_e32 v120, v119, v118
	v_fma_f32 v121, -v117, v120, v119
	v_fmac_f32_e32 v120, v121, v118
	v_fma_f32 v117, -v117, v120, v119
	v_div_fmas_f32 v117, v117, v118, v120
	v_div_fixup_f32 v116, v117, v116, 1.0
	v_pk_mul_f32 v[110:111], v[110:111], v[116:117] op_sel_hi:[1,0]
	v_pk_mul_f32 v[106:107], v[106:107], v[116:117] op_sel_hi:[1,0]
	v_pk_mul_f32 v[112:113], v[112:113], v[116:117] op_sel_hi:[1,0]
	v_pk_mul_f32 v[108:109], v[108:109], v[116:117] op_sel_hi:[1,0]
	v_max_f32_e32 v110, 0, v110
	v_max_f32_e32 v106, 0, v106
	v_max_f32_e32 v111, 0, v111
	v_max_f32_e32 v107, 0, v107
	v_pk_mul_f32 v[110:111], v[110:111], v[110:111]
	v_pk_mul_f32 v[118:119], v[106:107], v[106:107]
	v_max_f32_e32 v106, 0, v112
	v_max_f32_e32 v108, 0, v108
	v_max_f32_e32 v107, 0, v113
	v_max_f32_e32 v109, 0, v109
	v_pk_mul_f32 v[112:113], v[106:107], v[106:107]
	v_pk_mul_f32 v[120:121], v[108:109], v[108:109]
	v_cvt_pk_bf16_f32 v106, v110, v111
	v_lshl_add_u64 v[110:111], s[92:93], 0, v[114:115]
	v_pk_mul_f32 v[98:99], v[98:99], v[116:117] op_sel_hi:[1,0]
	v_cvt_pk_bf16_f32 v107, v112, v113
	v_cvt_pk_bf16_f32 v108, v118, v119
	v_cvt_pk_bf16_f32 v109, v120, v121
	v_lshl_add_u64 v[110:111], v[110:111], 0, v[122:123]
	v_pk_mul_f32 v[104:105], v[104:105], v[116:117] op_sel_hi:[1,0]
	v_pk_mul_f32 v[102:103], v[102:103], v[116:117] op_sel_hi:[1,0]
	v_pk_mul_f32 v[100:101], v[100:101], v[116:117] op_sel_hi:[1,0]
	v_max_f32_e32 v98, 0, v98
	v_max_f32_e32 v99, 0, v99
	global_store_dwordx4 v[110:111], v[106:109], off
	v_max_f32_e32 v102, 0, v102
	v_max_f32_e32 v103, 0, v103
	v_pk_mul_f32 v[106:107], v[98:99], v[98:99]
	v_max_f32_e32 v98, 0, v104
	v_max_f32_e32 v100, 0, v100
	v_max_f32_e32 v99, 0, v105
	v_max_f32_e32 v101, 0, v101
	v_pk_mul_f32 v[102:103], v[102:103], v[102:103]
	v_pk_mul_f32 v[104:105], v[98:99], v[98:99]
	v_pk_mul_f32 v[108:109], v[100:101], v[100:101]
	v_cvt_pk_bf16_f32 v98, v102, v103
	v_cvt_pk_bf16_f32 v99, v104, v105
	v_cvt_pk_bf16_f32 v100, v106, v107
	v_cvt_pk_bf16_f32 v101, v108, v109
	global_store_dwordx4 v[110:111], v[98:101], off offset:256
	s_nop 1
	v_or_b32_e32 v98, 32, v158
	v_ashrrev_i32_e32 v99, 31, v98
	v_lshlrev_b64 v[100:101], 7, v[98:99]
	v_lshl_add_u64 v[100:101], v[152:153], 0, v[100:101]
	v_lshlrev_b64 v[98:99], 14, v[98:99]
	s_waitcnt vmcnt(12)
	v_mov_b32_e32 v102, v212
	v_mov_b32_e32 v103, v213
	v_mov_b32_e32 v104, v214
	v_mov_b32_e32 v105, v215
	v_mov_b32_e32 v106, v216
	v_mov_b32_e32 v107, v217
	v_mov_b32_e32 v108, v218
	v_mov_b32_e32 v109, v219
	v_mov_b32_e32 v100, v102
	v_mov_b32_e32 v101, v106
	v_mov_b32_e32 v106, v103
	v_mov_b32_e32 v102, v104
	v_mov_b32_e32 v103, v108
	v_mov_b32_e32 v108, v105
	v_pk_add_f32 v[100:101], v[100:101], v[106:107]
	v_pk_add_f32 v[102:103], v[102:103], v[108:109]
	s_nop 0
	v_pk_add_f32 v[100:101], v[100:101], v[102:103]
	s_nop 0
	v_add_f32_e32 v100, v100, v101
	ds_bpermute_b32 v101, v162, v100
	s_waitcnt lgkmcnt(0)
	v_add_f32_e32 v100, v100, v101
	ds_bpermute_b32 v101, v163, v100
	s_waitcnt lgkmcnt(0)
; __device__ __forceinline__ unsigned cvt_pk_bf16(float lo, float hi) { const f32x2c_t v = {lo, hi}; const bf16x2c_t b = __builtin_convertvector(v, bf16x2c_t); return __builtin_bit_cast(unsigned, b); }
;     __device__ __forceinline__ void operator()(const f32x4 (&acc)[2][2][4][2], const Unit& u, int wr, int wc, int fr, int fq) const {
;     ...
;             for (int m = 0; m < 4; ++m) { const size_t row = (size_t)(row0 + ai * HALF + m * 16);
;                 const f32x4* sp = (const f32x4*)(SS + row * 32) + 2 * fq; float s;
;                 { const f32x4 t0 = sp[0], t1 = sp[1]; s = ((t0[0] + t0[1]) + (t0[2] + t0[3])) + ((t1[0] + t1[1]) + (t1[2] + t1[3])); }
;                 s += __shfl_xor(s, 16); s += __shfl_xor(s, 32);
;                 const float rstd = 1.0f / sqrtf(s * (1.0f / DM) + NORM_EPS);
; #pragma unroll
;                 for (int bj = 0; bj < 2; ++bj) { f32x4 v0 = acc[ai][bj][m][0] * rstd, v1 = acc[ai][bj][m][1] * rstd;
; #pragma unroll
;                     for (int e = 0; e < 4; ++e) { const float a = fmaxf(v0[e], 0.f), b = fmaxf(v1[e], 0.f); v0[e] = a * a; v1[e] = b * b; }
;                     u32x4 w; w.x = cvt_pk_bf16(v0[0], v0[1]); w.y = cvt_pk_bf16(v0[2], v0[3]); w.z = cvt_pk_bf16(v1[0], v1[1]); w.w = cvt_pk_bf16(v1[2], v1[3]);
;                     *(u32x4*)(H + row * DFF + col0 + bj * HALF) = w; } }
	v_add_f32_e32 v100, v100, v101
	v_fmamk_f32 v100, v100, 0x3a000000, v190
	v_cmp_gt_f32_e32 vcc, s72, v100
	v_mul_f32_e32 v101, 0x4f800000, v100
	s_nop 0
	v_cndmask_b32_e32 v100, v100, v101, vcc
	v_sqrt_f32_e32 v101, v100
	s_nop 0
	v_add_u32_e32 v102, -1, v101
	v_fma_f32 v103, -v102, v101, v100
	v_cmp_ge_f32_e64 s[0:1], 0, v103
	v_add_u32_e32 v103, 1, v101
	s_nop 0
	v_cndmask_b32_e64 v102, v101, v102, s[0:1]
	v_fma_f32 v101, -v103, v101, v100
	v_cmp_lt_f32_e64 s[0:1], 0, v101
	s_nop 1
	v_cndmask_b32_e64 v101, v102, v103, s[0:1]
	v_mul_f32_e32 v102, 0x37800000, v101
	v_cndmask_b32_e32 v101, v101, v102, vcc
	v_cmp_class_f32_e32 vcc, v100, v191
	s_nop 1
	v_cndmask_b32_e32 v100, v101, v100, vcc
	v_div_scale_f32 v101, s[0:1], v100, v100, 1.0
	v_rcp_f32_e32 v102, v101
	s_nop 0
	v_fma_f32 v103, -v101, v102, 1.0
	v_fmac_f32_e32 v102, v103, v102
	v_div_scale_f32 v103, vcc, 1.0, v100, 1.0
	v_mul_f32_e32 v104, v103, v102
	v_fma_f32 v105, -v101, v104, v103
	v_fmac_f32_e32 v104, v105, v102
	v_fma_f32 v101, -v101, v104, v103
	v_div_fmas_f32 v101, v101, v102, v104
	v_div_fixup_f32 v100, v101, v100, 1.0
	v_pk_mul_f32 v[94:95], v[94:95], v[100:101] op_sel_hi:[1,0]
	v_pk_mul_f32 v[90:91], v[90:91], v[100:101] op_sel_hi:[1,0]
	v_pk_mul_f32 v[96:97], v[96:97], v[100:101] op_sel_hi:[1,0]
	v_pk_mul_f32 v[92:93], v[92:93], v[100:101] op_sel_hi:[1,0]
	v_max_f32_e32 v94, 0, v94
	v_max_f32_e32 v90, 0, v90
	v_max_f32_e32 v95, 0, v95
	v_max_f32_e32 v91, 0, v91
	v_pk_mul_f32 v[94:95], v[94:95], v[94:95]
	v_pk_mul_f32 v[102:103], v[90:91], v[90:91]
	v_max_f32_e32 v90, 0, v96
	v_max_f32_e32 v92, 0, v92
	v_max_f32_e32 v91, 0, v97
	v_max_f32_e32 v93, 0, v93
	v_pk_mul_f32 v[96:97], v[90:91], v[90:91]
	v_pk_mul_f32 v[104:105], v[92:93], v[92:93]
	v_cvt_pk_bf16_f32 v90, v94, v95
	v_lshl_add_u64 v[94:95], s[92:93], 0, v[98:99]
	v_pk_mul_f32 v[82:83], v[82:83], v[100:101] op_sel_hi:[1,0]
	v_cvt_pk_bf16_f32 v91, v96, v97
	v_cvt_pk_bf16_f32 v92, v102, v103
	v_cvt_pk_bf16_f32 v93, v104, v105
	v_lshl_add_u64 v[94:95], v[94:95], 0, v[122:123]
	v_pk_mul_f32 v[88:89], v[88:89], v[100:101] op_sel_hi:[1,0]
	v_pk_mul_f32 v[86:87], v[86:87], v[100:101] op_sel_hi:[1,0]
	v_pk_mul_f32 v[84:85], v[84:85], v[100:101] op_sel_hi:[1,0]
	v_max_f32_e32 v82, 0, v82
	v_max_f32_e32 v83, 0, v83
	global_store_dwordx4 v[94:95], v[90:93], off
	v_max_f32_e32 v86, 0, v86
	v_max_f32_e32 v87, 0, v87
	v_pk_mul_f32 v[90:91], v[82:83], v[82:83]
	v_max_f32_e32 v82, 0, v88
	v_max_f32_e32 v84, 0, v84
	v_max_f32_e32 v83, 0, v89
	v_max_f32_e32 v85, 0, v85
	v_pk_mul_f32 v[86:87], v[86:87], v[86:87]
	v_pk_mul_f32 v[88:89], v[82:83], v[82:83]
	v_pk_mul_f32 v[92:93], v[84:85], v[84:85]
	v_cvt_pk_bf16_f32 v82, v86, v87
	v_cvt_pk_bf16_f32 v83, v88, v89
	v_cvt_pk_bf16_f32 v84, v90, v91
	v_cvt_pk_bf16_f32 v85, v92, v93
	global_store_dwordx4 v[94:95], v[82:85], off offset:256
	s_nop 1
	v_or_b32_e32 v82, 48, v158
	v_ashrrev_i32_e32 v83, 31, v82
	v_lshlrev_b64 v[84:85], 7, v[82:83]
	v_lshl_add_u64 v[84:85], v[152:153], 0, v[84:85]
	v_lshlrev_b64 v[82:83], 14, v[82:83]
	s_waitcnt vmcnt(12)
	v_mov_b32_e32 v86, v220
	v_mov_b32_e32 v87, v221
	v_mov_b32_e32 v88, v222
	v_mov_b32_e32 v89, v223
	v_mov_b32_e32 v90, v224
	v_mov_b32_e32 v91, v225
	v_mov_b32_e32 v92, v226
	v_mov_b32_e32 v93, v227
	v_mov_b32_e32 v84, v86
	v_mov_b32_e32 v85, v90
	v_mov_b32_e32 v90, v87
	v_mov_b32_e32 v86, v88
	v_mov_b32_e32 v87, v92
	v_mov_b32_e32 v92, v89
	v_pk_add_f32 v[84:85], v[84:85], v[90:91]
	v_pk_add_f32 v[86:87], v[86:87], v[92:93]
	s_nop 0
	v_pk_add_f32 v[84:85], v[84:85], v[86:87]
	s_nop 0
	v_add_f32_e32 v84, v84, v85
	ds_bpermute_b32 v85, v162, v84
	s_waitcnt lgkmcnt(0)
	v_add_f32_e32 v84, v84, v85
	ds_bpermute_b32 v85, v163, v84
	s_waitcnt lgkmcnt(0)
	v_add_f32_e32 v84, v84, v85
	v_fmamk_f32 v84, v84, 0x3a000000, v190
	v_cmp_gt_f32_e32 vcc, s72, v84
	v_mul_f32_e32 v85, 0x4f800000, v84
	s_nop 0
	v_cndmask_b32_e32 v84, v84, v85, vcc
	v_sqrt_f32_e32 v85, v84
	s_nop 0
	v_add_u32_e32 v86, -1, v85
	v_fma_f32 v87, -v86, v85, v84
	v_cmp_ge_f32_e64 s[0:1], 0, v87
	v_add_u32_e32 v87, 1, v85
	s_nop 0
	v_cndmask_b32_e64 v86, v85, v86, s[0:1]
	v_fma_f32 v85, -v87, v85, v84
	v_cmp_lt_f32_e64 s[0:1], 0, v85
	s_nop 1
	v_cndmask_b32_e64 v85, v86, v87, s[0:1]
	v_mul_f32_e32 v86, 0x37800000, v85
	v_cndmask_b32_e32 v85, v85, v86, vcc
	v_cmp_class_f32_e32 vcc, v84, v191
	s_nop 1
	v_cndmask_b32_e32 v84, v85, v84, vcc
	v_div_scale_f32 v85, s[0:1], v84, v84, 1.0
	v_rcp_f32_e32 v86, v85
	s_nop 0
	v_fma_f32 v87, -v85, v86, 1.0
	v_fmac_f32_e32 v86, v87, v86
	v_div_scale_f32 v87, vcc, 1.0, v84, 1.0
	v_mul_f32_e32 v88, v87, v86
	v_fma_f32 v89, -v85, v88, v87
	v_fmac_f32_e32 v88, v89, v86
	v_fma_f32 v85, -v85, v88, v87
	v_div_fmas_f32 v85, v85, v86, v88
	v_div_fixup_f32 v84, v85, v84, 1.0
	v_pk_mul_f32 v[78:79], v[78:79], v[84:85] op_sel_hi:[1,0]
	v_pk_mul_f32 v[74:75], v[74:75], v[84:85] op_sel_hi:[1,0]
	v_pk_mul_f32 v[80:81], v[80:81], v[84:85] op_sel_hi:[1,0]
	v_pk_mul_f32 v[76:77], v[76:77], v[84:85] op_sel_hi:[1,0]
	v_max_f32_e32 v78, 0, v78
	v_max_f32_e32 v74, 0, v74
	v_max_f32_e32 v79, 0, v79
	v_max_f32_e32 v75, 0, v75
	v_pk_mul_f32 v[78:79], v[78:79], v[78:79]
	v_pk_mul_f32 v[86:87], v[74:75], v[74:75]
	v_max_f32_e32 v74, 0, v80
	v_max_f32_e32 v76, 0, v76
	v_max_f32_e32 v75, 0, v81
	v_max_f32_e32 v77, 0, v77
	v_pk_mul_f32 v[80:81], v[74:75], v[74:75]
	v_pk_mul_f32 v[88:89], v[76:77], v[76:77]
	v_cvt_pk_bf16_f32 v74, v78, v79
	v_lshl_add_u64 v[78:79], s[92:93], 0, v[82:83]
	v_pk_mul_f32 v[66:67], v[66:67], v[84:85] op_sel_hi:[1,0]
	v_cvt_pk_bf16_f32 v75, v80, v81
	v_cvt_pk_bf16_f32 v76, v86, v87
	v_cvt_pk_bf16_f32 v77, v88, v89
	v_lshl_add_u64 v[78:79], v[78:79], 0, v[122:123]
	v_pk_mul_f32 v[72:73], v[72:73], v[84:85] op_sel_hi:[1,0]
	v_pk_mul_f32 v[70:71], v[70:71], v[84:85] op_sel_hi:[1,0]
	v_pk_mul_f32 v[68:69], v[68:69], v[84:85] op_sel_hi:[1,0]
	v_max_f32_e32 v66, 0, v66
	v_max_f32_e32 v67, 0, v67
	global_store_dwordx4 v[78:79], v[74:77], off
	v_max_f32_e32 v70, 0, v70
	v_max_f32_e32 v71, 0, v71
	v_pk_mul_f32 v[74:75], v[66:67], v[66:67]
	v_max_f32_e32 v66, 0, v72
	v_max_f32_e32 v68, 0, v68
	v_max_f32_e32 v67, 0, v73
	v_max_f32_e32 v69, 0, v69
	v_pk_mul_f32 v[70:71], v[70:71], v[70:71]
	v_pk_mul_f32 v[72:73], v[66:67], v[66:67]
	v_pk_mul_f32 v[76:77], v[68:69], v[68:69]
	v_cvt_pk_bf16_f32 v66, v70, v71
	v_cvt_pk_bf16_f32 v67, v72, v73
	v_cvt_pk_bf16_f32 v68, v74, v75
	v_cvt_pk_bf16_f32 v69, v76, v77
	global_store_dwordx4 v[78:79], v[66:69], off offset:256
	s_nop 1
	v_add_u32_e32 v66, 0x80, v158
	v_ashrrev_i32_e32 v67, 31, v66
	v_lshlrev_b64 v[68:69], 7, v[66:67]
	v_lshl_add_u64 v[68:69], v[152:153], 0, v[68:69]
	v_lshlrev_b64 v[66:67], 14, v[66:67]
	s_waitcnt vmcnt(12)
; __device__ __forceinline__ unsigned cvt_pk_bf16(float lo, float hi) { const f32x2c_t v = {lo, hi}; const bf16x2c_t b = __builtin_convertvector(v, bf16x2c_t); return __builtin_bit_cast(unsigned, b); }
;     __device__ __forceinline__ void operator()(const f32x4 (&acc)[2][2][4][2], const Unit& u, int wr, int wc, int fr, int fq) const {
;     ...
;             for (int m = 0; m < 4; ++m) { const size_t row = (size_t)(row0 + ai * HALF + m * 16);
;                 const f32x4* sp = (const f32x4*)(SS + row * 32) + 2 * fq; float s;
;                 { const f32x4 t0 = sp[0], t1 = sp[1]; s = ((t0[0] + t0[1]) + (t0[2] + t0[3])) + ((t1[0] + t1[1]) + (t1[2] + t1[3])); }
;                 s += __shfl_xor(s, 16); s += __shfl_xor(s, 32);
;                 const float rstd = 1.0f / sqrtf(s * (1.0f / DM) + NORM_EPS);
; #pragma unroll
;                 for (int bj = 0; bj < 2; ++bj) { f32x4 v0 = acc[ai][bj][m][0] * rstd, v1 = acc[ai][bj][m][1] * rstd;
; #pragma unroll
;                     for (int e = 0; e < 4; ++e) { const float a = fmaxf(v0[e], 0.f), b = fmaxf(v1[e], 0.f); v0[e] = a * a; v1[e] = b * b; }
;                     u32x4 w; w.x = cvt_pk_bf16(v0[0], v0[1]); w.y = cvt_pk_bf16(v0[2], v0[3]); w.z = cvt_pk_bf16(v1[0], v1[1]); w.w = cvt_pk_bf16(v1[2], v1[3]);
;                     *(u32x4*)(H + row * DFF + col0 + bj * HALF) = w; } }
	v_mov_b32_e32 v70, v228
	v_mov_b32_e32 v71, v229
	v_mov_b32_e32 v72, v230
	v_mov_b32_e32 v73, v231
	v_mov_b32_e32 v74, v232
	v_mov_b32_e32 v75, v233
	v_mov_b32_e32 v76, v234
	v_mov_b32_e32 v77, v235
	v_mov_b32_e32 v68, v70
	v_mov_b32_e32 v69, v74
	v_mov_b32_e32 v74, v71
	v_mov_b32_e32 v70, v72
	v_mov_b32_e32 v71, v76
	v_mov_b32_e32 v76, v73
	v_pk_add_f32 v[68:69], v[68:69], v[74:75]
	v_pk_add_f32 v[70:71], v[70:71], v[76:77]
	s_nop 0
	v_pk_add_f32 v[68:69], v[68:69], v[70:71]
	s_nop 0
	v_add_f32_e32 v68, v68, v69
	ds_bpermute_b32 v69, v162, v68
	s_waitcnt lgkmcnt(0)
	v_add_f32_e32 v68, v68, v69
	ds_bpermute_b32 v69, v163, v68
	s_waitcnt lgkmcnt(0)
	v_add_f32_e32 v68, v68, v69
	v_fmamk_f32 v68, v68, 0x3a000000, v190
	v_cmp_gt_f32_e32 vcc, s72, v68
	v_mul_f32_e32 v69, 0x4f800000, v68
	s_nop 0
	v_cndmask_b32_e32 v68, v68, v69, vcc
	v_sqrt_f32_e32 v69, v68
	s_nop 0
	v_add_u32_e32 v70, -1, v69
	v_fma_f32 v71, -v70, v69, v68
	v_cmp_ge_f32_e64 s[0:1], 0, v71
	v_add_u32_e32 v71, 1, v69
	s_nop 0
	v_cndmask_b32_e64 v70, v69, v70, s[0:1]
	v_fma_f32 v69, -v71, v69, v68
	v_cmp_lt_f32_e64 s[0:1], 0, v69
	s_nop 1
	v_cndmask_b32_e64 v69, v70, v71, s[0:1]
	v_mul_f32_e32 v70, 0x37800000, v69
	v_cndmask_b32_e32 v69, v69, v70, vcc
	v_cmp_class_f32_e32 vcc, v68, v191
	s_nop 1
	v_cndmask_b32_e32 v68, v69, v68, vcc
	v_div_scale_f32 v69, s[0:1], v68, v68, 1.0
	v_rcp_f32_e32 v70, v69
	s_nop 0
	v_fma_f32 v71, -v69, v70, 1.0
	v_fmac_f32_e32 v70, v71, v70
	v_div_scale_f32 v71, vcc, 1.0, v68, 1.0
	v_mul_f32_e32 v72, v71, v70
	v_fma_f32 v73, -v69, v72, v71
	v_fmac_f32_e32 v72, v73, v70
	v_fma_f32 v69, -v69, v72, v71
	v_div_fmas_f32 v69, v69, v70, v72
	v_div_fixup_f32 v68, v69, v68, 1.0
	v_pk_mul_f32 v[62:63], v[62:63], v[68:69] op_sel_hi:[1,0]
	v_pk_mul_f32 v[58:59], v[58:59], v[68:69] op_sel_hi:[1,0]
	v_pk_mul_f32 v[64:65], v[64:65], v[68:69] op_sel_hi:[1,0]
	v_pk_mul_f32 v[60:61], v[60:61], v[68:69] op_sel_hi:[1,0]
	v_max_f32_e32 v62, 0, v62
	v_max_f32_e32 v58, 0, v58
	v_max_f32_e32 v63, 0, v63
	v_max_f32_e32 v59, 0, v59
	v_pk_mul_f32 v[62:63], v[62:63], v[62:63]
	v_pk_mul_f32 v[70:71], v[58:59], v[58:59]
	v_max_f32_e32 v58, 0, v64
	v_max_f32_e32 v60, 0, v60
	v_max_f32_e32 v59, 0, v65
	v_max_f32_e32 v61, 0, v61
	v_pk_mul_f32 v[64:65], v[58:59], v[58:59]
	v_pk_mul_f32 v[72:73], v[60:61], v[60:61]
	v_cvt_pk_bf16_f32 v58, v62, v63
	v_lshl_add_u64 v[62:63], s[92:93], 0, v[66:67]
	v_pk_mul_f32 v[50:51], v[50:51], v[68:69] op_sel_hi:[1,0]
	v_cvt_pk_bf16_f32 v59, v64, v65
	v_cvt_pk_bf16_f32 v60, v70, v71
	v_cvt_pk_bf16_f32 v61, v72, v73
	v_lshl_add_u64 v[62:63], v[62:63], 0, v[122:123]
	v_pk_mul_f32 v[56:57], v[56:57], v[68:69] op_sel_hi:[1,0]
	v_pk_mul_f32 v[54:55], v[54:55], v[68:69] op_sel_hi:[1,0]
	v_pk_mul_f32 v[52:53], v[52:53], v[68:69] op_sel_hi:[1,0]
	v_max_f32_e32 v50, 0, v50
	v_max_f32_e32 v51, 0, v51
	global_store_dwordx4 v[62:63], v[58:61], off
	v_max_f32_e32 v54, 0, v54
	v_max_f32_e32 v55, 0, v55
	v_pk_mul_f32 v[58:59], v[50:51], v[50:51]
	v_max_f32_e32 v50, 0, v56
	v_max_f32_e32 v52, 0, v52
	v_max_f32_e32 v51, 0, v57
	v_max_f32_e32 v53, 0, v53
	v_pk_mul_f32 v[54:55], v[54:55], v[54:55]
	v_pk_mul_f32 v[56:57], v[50:51], v[50:51]
	v_pk_mul_f32 v[60:61], v[52:53], v[52:53]
	v_cvt_pk_bf16_f32 v50, v54, v55
	v_cvt_pk_bf16_f32 v51, v56, v57
	v_cvt_pk_bf16_f32 v52, v58, v59
	v_cvt_pk_bf16_f32 v53, v60, v61
	global_store_dwordx4 v[62:63], v[50:53], off offset:256
	s_nop 1
	v_add_u32_e32 v50, 0x90, v158
	v_ashrrev_i32_e32 v51, 31, v50
	v_lshlrev_b64 v[52:53], 7, v[50:51]
	v_lshl_add_u64 v[52:53], v[152:153], 0, v[52:53]
	v_lshlrev_b64 v[50:51], 14, v[50:51]
	s_waitcnt vmcnt(12)
	v_mov_b32_e32 v54, v236
	v_mov_b32_e32 v55, v237
	v_mov_b32_e32 v56, v238
	v_mov_b32_e32 v57, v239
	v_mov_b32_e32 v58, v240
	v_mov_b32_e32 v59, v241
	v_mov_b32_e32 v60, v242
	v_mov_b32_e32 v61, v243
	v_mov_b32_e32 v52, v54
	v_mov_b32_e32 v53, v58
	v_mov_b32_e32 v58, v55
	v_mov_b32_e32 v54, v56
	v_mov_b32_e32 v55, v60
	v_mov_b32_e32 v60, v57
	v_pk_add_f32 v[52:53], v[52:53], v[58:59]
	v_pk_add_f32 v[54:55], v[54:55], v[60:61]
	s_nop 0
	v_pk_add_f32 v[52:53], v[52:53], v[54:55]
	s_nop 0
	v_add_f32_e32 v52, v52, v53
	ds_bpermute_b32 v53, v162, v52
	s_waitcnt lgkmcnt(0)
	v_add_f32_e32 v52, v52, v53
	ds_bpermute_b32 v53, v163, v52
	s_waitcnt lgkmcnt(0)
; __device__ __forceinline__ unsigned cvt_pk_bf16(float lo, float hi) { const f32x2c_t v = {lo, hi}; const bf16x2c_t b = __builtin_convertvector(v, bf16x2c_t); return __builtin_bit_cast(unsigned, b); }
;     __device__ __forceinline__ void operator()(const f32x4 (&acc)[2][2][4][2], const Unit& u, int wr, int wc, int fr, int fq) const {
;     ...
;             for (int m = 0; m < 4; ++m) { const size_t row = (size_t)(row0 + ai * HALF + m * 16);
;                 const f32x4* sp = (const f32x4*)(SS + row * 32) + 2 * fq; float s;
;                 { const f32x4 t0 = sp[0], t1 = sp[1]; s = ((t0[0] + t0[1]) + (t0[2] + t0[3])) + ((t1[0] + t1[1]) + (t1[2] + t1[3])); }
;                 s += __shfl_xor(s, 16); s += __shfl_xor(s, 32);
;                 const float rstd = 1.0f / sqrtf(s * (1.0f / DM) + NORM_EPS);
; #pragma unroll
;                 for (int bj = 0; bj < 2; ++bj) { f32x4 v0 = acc[ai][bj][m][0] * rstd, v1 = acc[ai][bj][m][1] * rstd;
; #pragma unroll
;                     for (int e = 0; e < 4; ++e) { const float a = fmaxf(v0[e], 0.f), b = fmaxf(v1[e], 0.f); v0[e] = a * a; v1[e] = b * b; }
;                     u32x4 w; w.x = cvt_pk_bf16(v0[0], v0[1]); w.y = cvt_pk_bf16(v0[2], v0[3]); w.z = cvt_pk_bf16(v1[0], v1[1]); w.w = cvt_pk_bf16(v1[2], v1[3]);
;                     *(u32x4*)(H + row * DFF + col0 + bj * HALF) = w; } }
	v_add_f32_e32 v52, v52, v53
	v_fmamk_f32 v52, v52, 0x3a000000, v190
	v_cmp_gt_f32_e32 vcc, s72, v52
	v_mul_f32_e32 v53, 0x4f800000, v52
	s_nop 0
	v_cndmask_b32_e32 v52, v52, v53, vcc
	v_sqrt_f32_e32 v53, v52
	s_nop 0
	v_add_u32_e32 v54, -1, v53
	v_fma_f32 v55, -v54, v53, v52
	v_cmp_ge_f32_e64 s[0:1], 0, v55
	v_add_u32_e32 v55, 1, v53
	s_nop 0
	v_cndmask_b32_e64 v54, v53, v54, s[0:1]
	v_fma_f32 v53, -v55, v53, v52
	v_cmp_lt_f32_e64 s[0:1], 0, v53
	s_nop 1
	v_cndmask_b32_e64 v53, v54, v55, s[0:1]
	v_mul_f32_e32 v54, 0x37800000, v53
	v_cndmask_b32_e32 v53, v53, v54, vcc
	v_cmp_class_f32_e32 vcc, v52, v191
	s_nop 1
	v_cndmask_b32_e32 v52, v53, v52, vcc
	v_div_scale_f32 v53, s[0:1], v52, v52, 1.0
	v_rcp_f32_e32 v54, v53
	s_nop 0
	v_fma_f32 v55, -v53, v54, 1.0
	v_fmac_f32_e32 v54, v55, v54
	v_div_scale_f32 v55, vcc, 1.0, v52, 1.0
	v_mul_f32_e32 v56, v55, v54
	v_fma_f32 v57, -v53, v56, v55
	v_fmac_f32_e32 v56, v57, v54
	v_fma_f32 v53, -v53, v56, v55
	v_div_fmas_f32 v53, v53, v54, v56
	v_div_fixup_f32 v52, v53, v52, 1.0
	v_pk_mul_f32 v[46:47], v[46:47], v[52:53] op_sel_hi:[1,0]
	v_pk_mul_f32 v[42:43], v[42:43], v[52:53] op_sel_hi:[1,0]
	v_pk_mul_f32 v[48:49], v[48:49], v[52:53] op_sel_hi:[1,0]
	v_pk_mul_f32 v[44:45], v[44:45], v[52:53] op_sel_hi:[1,0]
	v_max_f32_e32 v46, 0, v46
	v_max_f32_e32 v42, 0, v42
	v_max_f32_e32 v47, 0, v47
	v_max_f32_e32 v43, 0, v43
	v_pk_mul_f32 v[46:47], v[46:47], v[46:47]
	v_pk_mul_f32 v[54:55], v[42:43], v[42:43]
	v_max_f32_e32 v42, 0, v48
	v_max_f32_e32 v44, 0, v44
	v_max_f32_e32 v43, 0, v49
	v_max_f32_e32 v45, 0, v45
	v_pk_mul_f32 v[48:49], v[42:43], v[42:43]
	v_pk_mul_f32 v[56:57], v[44:45], v[44:45]
	v_cvt_pk_bf16_f32 v42, v46, v47
	v_lshl_add_u64 v[46:47], s[92:93], 0, v[50:51]
	v_pk_mul_f32 v[34:35], v[34:35], v[52:53] op_sel_hi:[1,0]
	v_cvt_pk_bf16_f32 v43, v48, v49
	v_cvt_pk_bf16_f32 v44, v54, v55
	v_cvt_pk_bf16_f32 v45, v56, v57
	v_lshl_add_u64 v[46:47], v[46:47], 0, v[122:123]
	v_pk_mul_f32 v[40:41], v[40:41], v[52:53] op_sel_hi:[1,0]
	v_pk_mul_f32 v[38:39], v[38:39], v[52:53] op_sel_hi:[1,0]
	v_pk_mul_f32 v[36:37], v[36:37], v[52:53] op_sel_hi:[1,0]
	v_max_f32_e32 v34, 0, v34
	v_max_f32_e32 v35, 0, v35
	global_store_dwordx4 v[46:47], v[42:45], off
	v_max_f32_e32 v38, 0, v38
	v_max_f32_e32 v39, 0, v39
	v_pk_mul_f32 v[42:43], v[34:35], v[34:35]
	v_max_f32_e32 v34, 0, v40
	v_max_f32_e32 v36, 0, v36
	v_max_f32_e32 v35, 0, v41
	v_max_f32_e32 v37, 0, v37
	v_pk_mul_f32 v[38:39], v[38:39], v[38:39]
	v_pk_mul_f32 v[40:41], v[34:35], v[34:35]
	v_pk_mul_f32 v[44:45], v[36:37], v[36:37]
	v_cvt_pk_bf16_f32 v34, v38, v39
	v_cvt_pk_bf16_f32 v35, v40, v41
	v_cvt_pk_bf16_f32 v36, v42, v43
	v_cvt_pk_bf16_f32 v37, v44, v45
	global_store_dwordx4 v[46:47], v[34:37], off offset:256
	s_nop 1
	v_add_u32_e32 v34, 0xa0, v158
	v_ashrrev_i32_e32 v35, 31, v34
	v_lshlrev_b64 v[36:37], 7, v[34:35]
	v_lshl_add_u64 v[36:37], v[152:153], 0, v[36:37]
	v_lshlrev_b64 v[34:35], 14, v[34:35]
	s_waitcnt vmcnt(12)
	v_mov_b32_e32 v38, v176
	v_mov_b32_e32 v39, v177
	v_mov_b32_e32 v40, v178
	v_mov_b32_e32 v41, v179
	v_mov_b32_e32 v42, v180
	v_mov_b32_e32 v43, v181
	v_mov_b32_e32 v44, v182
	v_mov_b32_e32 v45, v183
	v_mov_b32_e32 v36, v38
	v_mov_b32_e32 v37, v42
	v_mov_b32_e32 v42, v39
	v_mov_b32_e32 v38, v40
	v_mov_b32_e32 v39, v44
	v_mov_b32_e32 v44, v41
	v_pk_add_f32 v[36:37], v[36:37], v[42:43]
	v_pk_add_f32 v[38:39], v[38:39], v[44:45]
	s_nop 0
	v_pk_add_f32 v[36:37], v[36:37], v[38:39]
	s_nop 0
	v_add_f32_e32 v36, v36, v37
	ds_bpermute_b32 v37, v162, v36
	s_waitcnt lgkmcnt(0)
	v_add_f32_e32 v36, v36, v37
	ds_bpermute_b32 v37, v163, v36
	s_waitcnt lgkmcnt(0)
; __device__ __forceinline__ unsigned cvt_pk_bf16(float lo, float hi) { const f32x2c_t v = {lo, hi}; const bf16x2c_t b = __builtin_convertvector(v, bf16x2c_t); return __builtin_bit_cast(unsigned, b); }
; #define PG8_BAR __builtin_amdgcn_s_barrier()
;     __device__ __forceinline__ void operator()(const f32x4 (&acc)[2][2][4][2], const Unit& u, int wr, int wc, int fr, int fq) const {
;     ...
;             for (int m = 0; m < 4; ++m) { const size_t row = (size_t)(row0 + ai * HALF + m * 16);
;                 const f32x4* sp = (const f32x4*)(SS + row * 32) + 2 * fq; float s;
;                 { const f32x4 t0 = sp[0], t1 = sp[1]; s = ((t0[0] + t0[1]) + (t0[2] + t0[3])) + ((t1[0] + t1[1]) + (t1[2] + t1[3])); }
;                 s += __shfl_xor(s, 16); s += __shfl_xor(s, 32);
;                 const float rstd = 1.0f / sqrtf(s * (1.0f / DM) + NORM_EPS);
; #pragma unroll
;                 for (int bj = 0; bj < 2; ++bj) { f32x4 v0 = acc[ai][bj][m][0] * rstd, v1 = acc[ai][bj][m][1] * rstd;
; #pragma unroll
;                     for (int e = 0; e < 4; ++e) { const float a = fmaxf(v0[e], 0.f), b = fmaxf(v1[e], 0.f); v0[e] = a * a; v1[e] = b * b; }
;                     u32x4 w; w.x = cvt_pk_bf16(v0[0], v0[1]); w.y = cvt_pk_bf16(v0[2], v0[3]); w.z = cvt_pk_bf16(v1[0], v1[1]); w.w = cvt_pk_bf16(v1[2], v1[3]);
;                     *(u32x4*)(H + row * DFF + col0 + bj * HALF) = w; } }
; template <class Epi, class Sched, bool ALIGN_EPI = false, bool SP2 = false>
; __device__ __forceinline__ void gemm_phase(PG8_LAS unsigned char* lds, const Gemm g, const Sched& S, const Epi& E) {
;     ...
;         if (!has_next) break;
; #pragma unroll
;         for (int a = 0; a < 2; ++a)
; #pragma unroll
;             for (int b = 0; b < 2; ++b)
; #pragma unroll
;                 for (int m = 0; m < 4; ++m)
; #pragma unroll
;                     for (int n = 0; n < 2; ++n) acc[a][b][m][n] = (f32x4){0.f, 0.f, 0.f, 0.f};
;         cur = nxt; cA = nA; cB = nB; ++ui;
;         if constexpr (ALIGN_EPI) { if (wr == 1) PG8_BAR; }
	v_add_f32_e32 v36, v36, v37
	v_fmamk_f32 v36, v36, 0x3a000000, v190
	v_cmp_gt_f32_e32 vcc, s72, v36
	v_mul_f32_e32 v37, 0x4f800000, v36
	s_nop 0
	v_cndmask_b32_e32 v36, v36, v37, vcc
	v_sqrt_f32_e32 v37, v36
	s_nop 0
	v_add_u32_e32 v38, -1, v37
	v_fma_f32 v39, -v38, v37, v36
	v_cmp_ge_f32_e64 s[0:1], 0, v39
	v_add_u32_e32 v39, 1, v37
	s_nop 0
	v_cndmask_b32_e64 v38, v37, v38, s[0:1]
	v_fma_f32 v37, -v39, v37, v36
	v_cmp_lt_f32_e64 s[0:1], 0, v37
	s_nop 1
	v_cndmask_b32_e64 v37, v38, v39, s[0:1]
	v_mul_f32_e32 v38, 0x37800000, v37
	v_cndmask_b32_e32 v37, v37, v38, vcc
	v_cmp_class_f32_e32 vcc, v36, v191
	s_nop 1
	v_cndmask_b32_e32 v36, v37, v36, vcc
	v_div_scale_f32 v37, s[0:1], v36, v36, 1.0
	v_rcp_f32_e32 v38, v37
	s_nop 0
	v_fma_f32 v39, -v37, v38, 1.0
	v_fmac_f32_e32 v38, v39, v38
	v_div_scale_f32 v39, vcc, 1.0, v36, 1.0
	v_mul_f32_e32 v40, v39, v38
	v_fma_f32 v41, -v37, v40, v39
	v_fmac_f32_e32 v40, v41, v38
	v_fma_f32 v37, -v37, v40, v39
	v_div_fmas_f32 v37, v37, v38, v40
	v_div_fixup_f32 v36, v37, v36, 1.0
	v_pk_mul_f32 v[30:31], v[30:31], v[36:37] op_sel_hi:[1,0]
	v_pk_mul_f32 v[26:27], v[26:27], v[36:37] op_sel_hi:[1,0]
	v_pk_mul_f32 v[32:33], v[32:33], v[36:37] op_sel_hi:[1,0]
	v_pk_mul_f32 v[28:29], v[28:29], v[36:37] op_sel_hi:[1,0]
	v_max_f32_e32 v30, 0, v30
	v_max_f32_e32 v26, 0, v26
	v_max_f32_e32 v31, 0, v31
	v_max_f32_e32 v27, 0, v27
	v_pk_mul_f32 v[30:31], v[30:31], v[30:31]
	v_pk_mul_f32 v[38:39], v[26:27], v[26:27]
	v_max_f32_e32 v26, 0, v32
	v_max_f32_e32 v28, 0, v28
	v_max_f32_e32 v27, 0, v33
	v_max_f32_e32 v29, 0, v29
	v_pk_mul_f32 v[32:33], v[26:27], v[26:27]
	v_pk_mul_f32 v[40:41], v[28:29], v[28:29]
	v_cvt_pk_bf16_f32 v26, v30, v31
	v_lshl_add_u64 v[30:31], s[92:93], 0, v[34:35]
	v_pk_mul_f32 v[18:19], v[18:19], v[36:37] op_sel_hi:[1,0]
	v_cvt_pk_bf16_f32 v27, v32, v33
	v_cvt_pk_bf16_f32 v28, v38, v39
	v_cvt_pk_bf16_f32 v29, v40, v41
	v_lshl_add_u64 v[30:31], v[30:31], 0, v[122:123]
	v_pk_mul_f32 v[24:25], v[24:25], v[36:37] op_sel_hi:[1,0]
	v_pk_mul_f32 v[22:23], v[22:23], v[36:37] op_sel_hi:[1,0]
	v_pk_mul_f32 v[20:21], v[20:21], v[36:37] op_sel_hi:[1,0]
	v_max_f32_e32 v18, 0, v18
	v_max_f32_e32 v19, 0, v19
	global_store_dwordx4 v[30:31], v[26:29], off
	v_max_f32_e32 v22, 0, v22
	v_max_f32_e32 v23, 0, v23
	v_pk_mul_f32 v[26:27], v[18:19], v[18:19]
	v_max_f32_e32 v18, 0, v24
	v_max_f32_e32 v20, 0, v20
	v_max_f32_e32 v19, 0, v25
	v_max_f32_e32 v21, 0, v21
	v_pk_mul_f32 v[22:23], v[22:23], v[22:23]
	v_pk_mul_f32 v[24:25], v[18:19], v[18:19]
	v_pk_mul_f32 v[28:29], v[20:21], v[20:21]
	v_cvt_pk_bf16_f32 v18, v22, v23
	v_cvt_pk_bf16_f32 v19, v24, v25
	v_cvt_pk_bf16_f32 v20, v26, v27
	v_cvt_pk_bf16_f32 v21, v28, v29
	global_store_dwordx4 v[30:31], v[18:21], off offset:256
	s_nop 1
	v_add_u32_e32 v18, 0xb0, v158
	v_ashrrev_i32_e32 v19, 31, v18
	v_lshlrev_b64 v[20:21], 7, v[18:19]
	v_lshl_add_u64 v[20:21], v[152:153], 0, v[20:21]
	global_load_dwordx4 v[22:25], v[20:21], off
	global_load_dwordx4 v[26:29], v[20:21], off offset:16
	v_lshlrev_b64 v[18:19], 14, v[18:19]
	s_waitcnt vmcnt(1)
	v_mov_b32_e32 v20, v22
	s_waitcnt vmcnt(0)
	v_mov_b32_e32 v21, v26
	v_mov_b32_e32 v26, v23
	v_mov_b32_e32 v22, v24
	v_mov_b32_e32 v23, v28
	v_mov_b32_e32 v28, v25
	v_pk_add_f32 v[20:21], v[20:21], v[26:27]
	v_pk_add_f32 v[22:23], v[22:23], v[28:29]
	s_nop 0
	v_pk_add_f32 v[20:21], v[20:21], v[22:23]
	s_nop 0
	v_add_f32_e32 v20, v20, v21
	ds_bpermute_b32 v21, v162, v20
	s_waitcnt lgkmcnt(0)
	v_add_f32_e32 v20, v20, v21
	ds_bpermute_b32 v21, v163, v20
	s_waitcnt lgkmcnt(0)
	v_add_f32_e32 v20, v20, v21
	v_fmamk_f32 v20, v20, 0x3a000000, v190
	v_cmp_gt_f32_e32 vcc, s72, v20
	v_mul_f32_e32 v21, 0x4f800000, v20
	s_nop 0
	v_cndmask_b32_e32 v20, v20, v21, vcc
	v_sqrt_f32_e32 v21, v20
	s_nop 0
	v_add_u32_e32 v22, -1, v21
	v_fma_f32 v23, -v22, v21, v20
	v_cmp_ge_f32_e64 s[0:1], 0, v23
	v_add_u32_e32 v23, 1, v21
	s_nop 0
	v_cndmask_b32_e64 v22, v21, v22, s[0:1]
	v_fma_f32 v21, -v23, v21, v20
	v_cmp_lt_f32_e64 s[0:1], 0, v21
	s_nop 1
	v_cndmask_b32_e64 v21, v22, v23, s[0:1]
	v_mul_f32_e32 v22, 0x37800000, v21
	v_cndmask_b32_e32 v21, v21, v22, vcc
	v_cmp_class_f32_e32 vcc, v20, v191
	s_nop 1
	v_cndmask_b32_e32 v20, v21, v20, vcc
	v_div_scale_f32 v21, s[0:1], v20, v20, 1.0
	v_rcp_f32_e32 v22, v21
	s_mov_b64 s[0:1], -1
	v_fma_f32 v23, -v21, v22, 1.0
	v_fmac_f32_e32 v22, v23, v22
	v_div_scale_f32 v23, vcc, 1.0, v20, 1.0
	v_mul_f32_e32 v24, v23, v22
	v_fma_f32 v25, -v21, v24, v23
	v_fmac_f32_e32 v24, v25, v22
	v_fma_f32 v21, -v21, v24, v23
	v_div_fmas_f32 v21, v21, v22, v24
	v_div_fixup_f32 v20, v21, v20, 1.0
	v_pk_mul_f32 v[14:15], v[14:15], v[20:21] op_sel_hi:[1,0]
	v_pk_mul_f32 v[10:11], v[10:11], v[20:21] op_sel_hi:[1,0]
	v_pk_mul_f32 v[16:17], v[16:17], v[20:21] op_sel_hi:[1,0]
	v_pk_mul_f32 v[12:13], v[12:13], v[20:21] op_sel_hi:[1,0]
	v_max_f32_e32 v14, 0, v14
	v_max_f32_e32 v10, 0, v10
	v_max_f32_e32 v15, 0, v15
	v_max_f32_e32 v11, 0, v11
	v_pk_mul_f32 v[14:15], v[14:15], v[14:15]
	v_pk_mul_f32 v[22:23], v[10:11], v[10:11]
	v_max_f32_e32 v10, 0, v16
	v_max_f32_e32 v12, 0, v12
	v_max_f32_e32 v11, 0, v17
	v_max_f32_e32 v13, 0, v13
	v_pk_mul_f32 v[16:17], v[10:11], v[10:11]
	v_pk_mul_f32 v[24:25], v[12:13], v[12:13]
	v_cvt_pk_bf16_f32 v10, v14, v15
	v_lshl_add_u64 v[14:15], s[92:93], 0, v[18:19]
	v_pk_mul_f32 v[2:3], v[2:3], v[20:21] op_sel_hi:[1,0]
	v_cvt_pk_bf16_f32 v11, v16, v17
	v_cvt_pk_bf16_f32 v12, v22, v23
	v_cvt_pk_bf16_f32 v13, v24, v25
	v_lshl_add_u64 v[14:15], v[14:15], 0, v[122:123]
	v_pk_mul_f32 v[8:9], v[8:9], v[20:21] op_sel_hi:[1,0]
	v_pk_mul_f32 v[6:7], v[6:7], v[20:21] op_sel_hi:[1,0]
	v_pk_mul_f32 v[4:5], v[4:5], v[20:21] op_sel_hi:[1,0]
	v_max_f32_e32 v2, 0, v2
	v_max_f32_e32 v3, 0, v3
	global_store_dwordx4 v[14:15], v[10:13], off
	v_max_f32_e32 v6, 0, v6
	v_max_f32_e32 v7, 0, v7
	v_pk_mul_f32 v[10:11], v[2:3], v[2:3]
	v_max_f32_e32 v2, 0, v8
	v_max_f32_e32 v4, 0, v4
	v_max_f32_e32 v3, 0, v9
	v_max_f32_e32 v5, 0, v5
	v_pk_mul_f32 v[6:7], v[6:7], v[6:7]
	v_pk_mul_f32 v[8:9], v[2:3], v[2:3]
	v_pk_mul_f32 v[12:13], v[4:5], v[4:5]
	v_cvt_pk_bf16_f32 v2, v6, v7
	v_cvt_pk_bf16_f32 v3, v8, v9
	v_cvt_pk_bf16_f32 v4, v10, v11
	v_cvt_pk_bf16_f32 v5, v12, v13
	s_andn2_b64 vcc, exec, s[40:41]
	global_store_dwordx4 v[14:15], v[2:5], off offset:256
	s_cbranch_vccnz .LBB0_68
	s_andn2_b64 vcc, exec, s[12:13]
	s_cbranch_vccnz .LBB0_67
	s_barrier
	s_branch .LBB0_67
